# v31 + weight-conversion items reordered so consecutive waves take consecutive k-blocks: each bf16 output row is written contiguously (write-through), f32 source read in column strips (nt)
# baseline (speedup 1.0000x reference)
; __device__ __forceinline__ void prologue(const Args& a, LAS unsigned char* lds, int wave, int lane) {
;     ...
;     for (int it = gw; it < DEPTH * I_L; it += NGW) {
;         const int l = it / I_L; int r = it % I_L;
;         unsigned char* wl = ws + WS_W + (size_t)l * W_L;
;         if (r < 2 * I_W1) {
;             const bool second = r >= I_W1; if (second) r -= I_W1;
;             const float* W = a.in[second ? 14 : 2] + (size_t)l * D * NFF; const float* ks = a.in[second ? 13 : 1] + (size_t)l * D;
;             const int nblk = NFF / 32, kb = r / nblk, nb = r % nblk, n0 = 32 * nb;
;             const int dst = n0 < DFF ? (n0 / 128) * 256 + (n0 % 128) : ((n0 - DFF) / 128) * 256 + 128 + ((n0 - DFF) % 128);
;             tr_item(W, D, NFF, ks, (bf16*)(wl + (second ? W3_OFF : W1_OFF)), dst, scr, 64 * kb, n0, lane);
;             continue;
;         }
;         r -= 2 * I_W1;
;         if (r < 2 * I_W2) {
;             const bool second = r >= I_W2; if (second) r -= I_W2;
;             const float* W = a.in[second ? 15 : 3] + (size_t)l * DFF * D;
;             const int nblk = D / 32, kb = r / nblk, nb = r % nblk;
;             tr_item(W, DFF, D, nullptr, (bf16*)(wl + (second ? W4_OFF : W2_OFF)), 32 * nb, scr, 64 * kb, 32 * nb, lane);
;             continue;
;         }
;         r -= 2 * I_W2;
;         if (r < I_WIN) {
;             const float* W = a.in[5] + (size_t)l * D * INCOLS; const float* ks = a.in[4] + (size_t)l * D;
;             const int nblk = NPROJ / 32, kb = r / nblk, nb = r % nblk;
;             tr_item(W, D, INCOLS, ks, (bf16*)(wl + WIN_OFF), 32 * nb, scr, 64 * kb, 32 * nb, lane);
;             continue;
;         }
;         r -= I_WIN;
;         {
;             const float* W = a.in[12] + (size_t)l * D * D;
;             const int nblk = D / 32, kb = r / nblk, nb = r % nblk;
;             tr_item(W, D, D, nullptr, (bf16*)(wl + WOUT_OFF), 32 * nb, scr, 64 * kb, 32 * nb, lane);
;         }
.LBB0_11:
	s_load_dwordx16 s[36:51], s[0:1], 0x0
	s_load_dwordx16 s[12:27], s[0:1], 0x40
	v_readlane_b32 s0, v230, 4
	s_lshr_b32 s97, s0, 6
	s_cmp_lt_i32 s52, 1
	s_cselect_b64 s[0:1], -1, 0
	s_cmp_gt_i32 s53, 0
	s_cselect_b64 s[2:3], -1, 0
	s_and_b64 s[62:63], s[0:1], s[2:3]
	s_andn2_b64 vcc, exec, s[62:63]
	v_and_b32_e32 v200, 63, v201
	s_cbranch_vccnz .LBB0_98
	s_lshl_b32 s0, s10, 3
	s_add_i32 s11, s97, s0
	s_cmpk_gt_i32 s11, 0x50ff
	s_cbranch_scc1 .LBB0_81
	s_waitcnt lgkmcnt(0)
	v_lshrrev_b32_e32 v1, 3, v200
	v_and_b32_e32 v3, 7, v200
	v_lshlrev_b32_e32 v2, 4, v3
	v_lshlrev_b32_e32 v4, 5, v3
	s_lshl_b32 s0, s97, 14
	v_mul_u32_u24_e32 v6, 0x84, v1
	v_add3_u32 v6, v6, v2, s0
	v_add_u32_e32 v7, 0x420, v6
	v_add_u32_e32 v8, 0x420, v7
	v_add_u32_e32 v9, 0x420, v8
	v_add_u32_e32 v10, 0x420, v9
	v_add_u32_e32 v11, 0x420, v10
	v_add_u32_e32 v12, 0x420, v11
	v_add_u32_e32 v13, 0x420, v12
	v_mul_u32_u24_e32 v5, 0x420, v3
	v_lshl_add_u32 v5, v1, 2, v5
	v_add_u32_e32 v5, s0, v5
	v_lshlrev_b32_e32 v3, 2, v3
	s_mov_b32 s83, s11
	s_cmp_ge_u32 s83, 0x2880
	s_cselect_b32 s0, 1, 0
	s_mul_i32 s1, s0, 0x2880
	s_sub_u32 s1, s83, s1
	s_mul_i32 s2, s0, 0x2880000
	s_add_u32 s68, s34, s2
	s_addc_u32 s69, s35, 0
	s_add_u32 s68, s68, 0x800000
	s_addc_u32 s69, s69, 0
	s_mov_b32 s31, 64
	s_cmp_lt_u32 s1, 0x1600
	s_cbranch_scc1 .Lwq_t0_0
	s_cmp_lt_u32 s1, 0x2100
	s_cbranch_scc1 .Lwq_t1_0
	s_cmp_lt_u32 s1, 0x2680
	s_cbranch_scc1 .Lwq_t2_0
	s_sub_u32 s1, s1, 0x2680
	s_and_b32 s3, s1, 15
	s_lshr_b32 s4, s1, 4
	s_lshl_b32 s5, s0, 22
	s_lshl_b32 s86, s3, 18
	s_add_u32 s5, s5, s86
	s_lshl_b32 s86, s4, 7
	s_add_u32 s5, s5, s86
	s_add_u32 s64, s20, s5
	s_addc_u32 s65, s21, 0
	s_mov_b32 s29, 0x1000
	s_mov_b32 s66, s38
	s_mov_b32 s67, s39
	s_mov_b32 s71, 0
	s_lshl_b32 s5, s4, 16
	s_lshl_b32 s86, s3, 7
	s_add_u32 s5, s5, s86
	s_add_u32 s5, s5, 0x1600000
	s_add_u32 s68, s68, s5
	s_addc_u32 s69, s69, 0
	s_mov_b32 s70, 0x800
	s_branch .Lwq_te_0
.Lwq_t1_0:
	s_sub_u32 s1, s1, 0x1600
	s_cmp_ge_u32 s1, 0x580
	s_cselect_b32 s2, 1, 0
	s_mul_i32 s3, s2, 0x580
	s_sub_u32 s1, s1, s3
	s_cmp_eq_u32 s2, 0
	s_cselect_b32 s64, s42, s26
	s_cselect_b32 s65, s43, s27
	s_mul_i32 s4, s1, 1490
	s_lshr_b32 s4, s4, 16
	s_mul_i32 s3, s4, 44
	s_sub_u32 s3, s1, s3
	s_mul_i32 s5, s0, 0xb00000
	s_lshl_b32 s86, s3, 18
	s_add_u32 s5, s5, s86
	s_lshl_b32 s86, s4, 7
	s_add_u32 s5, s5, s86
	s_add_u32 s64, s64, s5
	s_addc_u32 s65, s65, 0
	s_mov_b32 s29, 0x1000
	s_mov_b32 s66, s38
	s_mov_b32 s67, s39
	s_mov_b32 s71, 0
	s_mul_i32 s5, s2, 0x1800000
	s_add_u32 s5, s5, 0xb00000
	s_mul_i32 s86, s4, 0x2c000
	s_add_u32 s5, s5, s86
	s_lshl_b32 s86, s3, 7
	s_add_u32 s5, s5, s86
	s_add_u32 s68, s68, s5
	s_addc_u32 s69, s69, 0
	s_mov_b32 s70, 0x1600
	s_branch .Lwq_te_0
.Lwq_t2_0:
	s_sub_u32 s1, s1, 0x2100
	s_and_b32 s3, s1, 15
	s_lshr_b32 s4, s1, 4
	s_mul_i32 s5, s0, 0xa10000
	s_mul_i32 s86, s3, 0xa1000
	s_add_u32 s5, s5, s86
	s_lshl_b32 s86, s4, 7
	s_add_u32 s5, s5, s86
	s_add_u32 s64, s46, s5
	s_addc_u32 s65, s47, 0
	s_mov_b32 s29, 0x2840
	s_lshl_b32 s5, s0, 12
	s_lshl_b32 s86, s3, 8
	s_add_u32 s5, s5, s86
	s_add_u32 s66, s44, s5
	s_addc_u32 s67, s45, 0
	s_mov_b32 s71, 1
	s_lshl_b32 s86, s4, 5
	s_sub_u32 s31, 0xa10, s86
	s_lshl_b32 s5, s4, 16
	s_lshl_b32 s86, s3, 7
	s_add_u32 s5, s5, s86
	s_add_u32 s5, s5, 0x1080000
	s_add_u32 s68, s68, s5
	s_addc_u32 s69, s69, 0
	s_mov_b32 s70, 0x800
	s_branch .Lwq_te_0
.Lwq_t0_0:
	s_cmp_ge_u32 s1, 0xb00
	s_cselect_b32 s2, 1, 0
	s_mul_i32 s3, s2, 0xb00
	s_sub_u32 s1, s1, s3
	s_cmp_eq_u32 s2, 0
	s_cselect_b32 s64, s40, s24
	s_cselect_b32 s65, s41, s25
	s_cselect_b32 s66, s38, s22
	s_cselect_b32 s67, s39, s23
	s_and_b32 s3, s1, 15
	s_lshr_b32 s4, s1, 4
	s_mul_i32 s5, s0, 0x1600000
	s_mul_i32 s86, s3, 0x160000
	s_add_u32 s5, s5, s86
	s_lshl_b32 s86, s4, 7
	s_add_u32 s5, s5, s86
	s_add_u32 s64, s64, s5
	s_addc_u32 s65, s65, 0
	s_mov_b32 s29, 0x5800
	s_lshl_b32 s5, s0, 12
	s_lshl_b32 s86, s3, 8
	s_add_u32 s5, s5, s86
	s_add_u32 s66, s66, s5
	s_addc_u32 s67, s67, 0
	s_mov_b32 s71, 1
	s_lshl_b32 s86, s4, 5
	s_cmp_ge_u32 s86, 0xb00
	s_cselect_b32 s87, 0xb00, 0
	s_cselect_b32 s88, 128, 0
	s_sub_u32 s86, s86, s87
	s_lshr_b32 s87, s86, 7
	s_lshl_b32 s87, s87, 8
	s_and_b32 s86, s86, 127
	s_add_u32 s86, s86, s87
	s_add_u32 s86, s86, s88
	s_mul_i32 s5, s2, 0x1800000
	s_lshl_b32 s86, s86, 11
	s_add_u32 s5, s5, s86
	s_lshl_b32 s86, s3, 7
	s_add_u32 s5, s5, s86
	s_add_u32 s68, s68, s5
	s_addc_u32 s69, s69, 0
	s_mov_b32 s70, 0x800

; __device__ __forceinline__ void prologue(const Args& a, LAS unsigned char* lds, int wave, int lane) {
;     ...
;     for (int it = gw; it < DEPTH * I_L; it += NGW) {
;         const int l = it / I_L; int r = it % I_L;
;         unsigned char* wl = ws + WS_W + (size_t)l * W_L;
;         if (r < 2 * I_W1) {
;             const bool second = r >= I_W1; if (second) r -= I_W1;
;             const float* W = a.in[second ? 14 : 2] + (size_t)l * D * NFF; const float* ks = a.in[second ? 13 : 1] + (size_t)l * D;
;             const int nblk = NFF / 32, kb = r / nblk, nb = r % nblk, n0 = 32 * nb;
;             const int dst = n0 < DFF ? (n0 / 128) * 256 + (n0 % 128) : ((n0 - DFF) / 128) * 256 + 128 + ((n0 - DFF) % 128);
;             tr_item(W, D, NFF, ks, (bf16*)(wl + (second ? W3_OFF : W1_OFF)), dst, scr, 64 * kb, n0, lane);
;             continue;
;         }
;         r -= 2 * I_W1;
;         if (r < 2 * I_W2) {
;             const bool second = r >= I_W2; if (second) r -= I_W2;
;             const float* W = a.in[second ? 15 : 3] + (size_t)l * DFF * D;
;             const int nblk = D / 32, kb = r / nblk, nb = r % nblk;
;             tr_item(W, DFF, D, nullptr, (bf16*)(wl + (second ? W4_OFF : W2_OFF)), 32 * nb, scr, 64 * kb, 32 * nb, lane);
;             continue;
;         }
;         r -= 2 * I_W2;
;         if (r < I_WIN) {
;             const float* W = a.in[5] + (size_t)l * D * INCOLS; const float* ks = a.in[4] + (size_t)l * D;
;             const int nblk = NPROJ / 32, kb = r / nblk, nb = r % nblk;
;             tr_item(W, D, INCOLS, ks, (bf16*)(wl + WIN_OFF), 32 * nb, scr, 64 * kb, 32 * nb, lane);
;             continue;
;         }
;         r -= I_WIN;
;         {
;             const float* W = a.in[12] + (size_t)l * D * D;
;             const int nblk = D / 32, kb = r / nblk, nb = r % nblk;
;             tr_item(W, D, D, nullptr, (bf16*)(wl + WOUT_OFF), 32 * nb, scr, 64 * kb, 32 * nb, lane);
;         }
.Lwq_top0:
	s_lshl_b32 s82, s28, 3
	s_add_u32 s82, s83, s82
	s_cmp_lt_u32 s82, 0x5100
	s_cbranch_scc0 .Lwq_last0
	s_cmp_ge_u32 s82, 0x2880
	s_cselect_b32 s0, 1, 0
	s_mul_i32 s1, s0, 0x2880
	s_sub_u32 s1, s82, s1
	s_mul_i32 s2, s0, 0x2880000
	s_add_u32 s78, s34, s2
	s_addc_u32 s79, s35, 0
	s_add_u32 s78, s78, 0x800000
	s_addc_u32 s79, s79, 0
	s_mov_b32 s31, 64
	s_cmp_lt_u32 s1, 0x1600
	s_cbranch_scc1 .Lwq_t0_1
	s_cmp_lt_u32 s1, 0x2100
	s_cbranch_scc1 .Lwq_t1_1
	s_cmp_lt_u32 s1, 0x2680
	s_cbranch_scc1 .Lwq_t2_1
	s_sub_u32 s1, s1, 0x2680
	s_and_b32 s3, s1, 15
	s_lshr_b32 s4, s1, 4
	s_lshl_b32 s5, s0, 22
	s_lshl_b32 s86, s3, 18
	s_add_u32 s5, s5, s86
	s_lshl_b32 s86, s4, 7
	s_add_u32 s5, s5, s86
	s_add_u32 s74, s20, s5
	s_addc_u32 s75, s21, 0
	s_mov_b32 s29, 0x1000
	s_mov_b32 s76, s38
	s_mov_b32 s77, s39
	s_mov_b32 s81, 0
	s_lshl_b32 s5, s4, 16
	s_lshl_b32 s86, s3, 7
	s_add_u32 s5, s5, s86
	s_add_u32 s5, s5, 0x1600000
	s_add_u32 s78, s78, s5
	s_addc_u32 s79, s79, 0
	s_mov_b32 s80, 0x800
	s_branch .Lwq_te_1
.Lwq_t1_1:
	s_sub_u32 s1, s1, 0x1600
	s_cmp_ge_u32 s1, 0x580
	s_cselect_b32 s2, 1, 0
	s_mul_i32 s3, s2, 0x580
	s_sub_u32 s1, s1, s3
	s_cmp_eq_u32 s2, 0
	s_cselect_b32 s74, s42, s26
	s_cselect_b32 s75, s43, s27
	s_mul_i32 s4, s1, 1490
	s_lshr_b32 s4, s4, 16
	s_mul_i32 s3, s4, 44
	s_sub_u32 s3, s1, s3
	s_mul_i32 s5, s0, 0xb00000
	s_lshl_b32 s86, s3, 18
	s_add_u32 s5, s5, s86
	s_lshl_b32 s86, s4, 7
	s_add_u32 s5, s5, s86
	s_add_u32 s74, s74, s5
	s_addc_u32 s75, s75, 0
	s_mov_b32 s29, 0x1000
	s_mov_b32 s76, s38
	s_mov_b32 s77, s39
	s_mov_b32 s81, 0
	s_mul_i32 s5, s2, 0x1800000
	s_add_u32 s5, s5, 0xb00000
	s_mul_i32 s86, s4, 0x2c000
	s_add_u32 s5, s5, s86
	s_lshl_b32 s86, s3, 7
	s_add_u32 s5, s5, s86
	s_add_u32 s78, s78, s5
	s_addc_u32 s79, s79, 0
	s_mov_b32 s80, 0x1600
	s_branch .Lwq_te_1
.Lwq_t2_1:
	s_sub_u32 s1, s1, 0x2100
	s_and_b32 s3, s1, 15
	s_lshr_b32 s4, s1, 4
	s_mul_i32 s5, s0, 0xa10000
	s_mul_i32 s86, s3, 0xa1000
	s_add_u32 s5, s5, s86
	s_lshl_b32 s86, s4, 7
	s_add_u32 s5, s5, s86
	s_add_u32 s74, s46, s5
	s_addc_u32 s75, s47, 0
	s_mov_b32 s29, 0x2840
	s_lshl_b32 s5, s0, 12
	s_lshl_b32 s86, s3, 8
	s_add_u32 s5, s5, s86
	s_add_u32 s76, s44, s5
	s_addc_u32 s77, s45, 0
	s_mov_b32 s81, 1
	s_lshl_b32 s86, s4, 5
	s_sub_u32 s31, 0xa10, s86
	s_lshl_b32 s5, s4, 16
	s_lshl_b32 s86, s3, 7
	s_add_u32 s5, s5, s86
	s_add_u32 s5, s5, 0x1080000
	s_add_u32 s78, s78, s5
	s_addc_u32 s79, s79, 0
	s_mov_b32 s80, 0x800
	s_branch .Lwq_te_1
.Lwq_t0_1:
	s_cmp_ge_u32 s1, 0xb00
	s_cselect_b32 s2, 1, 0
	s_mul_i32 s3, s2, 0xb00
	s_sub_u32 s1, s1, s3
	s_cmp_eq_u32 s2, 0
	s_cselect_b32 s74, s40, s24
	s_cselect_b32 s75, s41, s25
	s_cselect_b32 s76, s38, s22
	s_cselect_b32 s77, s39, s23
	s_and_b32 s3, s1, 15
	s_lshr_b32 s4, s1, 4
	s_mul_i32 s5, s0, 0x1600000
	s_mul_i32 s86, s3, 0x160000
	s_add_u32 s5, s5, s86
	s_lshl_b32 s86, s4, 7
	s_add_u32 s5, s5, s86
	s_add_u32 s74, s74, s5
	s_addc_u32 s75, s75, 0
	s_mov_b32 s29, 0x5800
	s_lshl_b32 s5, s0, 12
	s_lshl_b32 s86, s3, 8
	s_add_u32 s5, s5, s86
	s_add_u32 s76, s76, s5
	s_addc_u32 s77, s77, 0
	s_mov_b32 s81, 1
	s_lshl_b32 s86, s4, 5
	s_cmp_ge_u32 s86, 0xb00
	s_cselect_b32 s87, 0xb00, 0
	s_cselect_b32 s88, 128, 0
	s_sub_u32 s86, s86, s87
	s_lshr_b32 s87, s86, 7
	s_lshl_b32 s87, s87, 8
	s_and_b32 s86, s86, 127
	s_add_u32 s86, s86, s87
	s_add_u32 s86, s86, s88
	s_mul_i32 s5, s2, 0x1800000
	s_lshl_b32 s86, s86, 11
	s_add_u32 s5, s5, s86
	s_lshl_b32 s86, s3, 7
	s_add_u32 s5, s5, s86
	s_add_u32 s78, s78, s5
	s_addc_u32 s79, s79, 0
	s_mov_b32 s80, 0x800

; __device__ __forceinline__ void prologue(const Args& a, LAS unsigned char* lds, int wave, int lane) {
;     ...
;     for (int it = gw; it < DEPTH * I_L; it += NGW) {
;         const int l = it / I_L; int r = it % I_L;
;         unsigned char* wl = ws + WS_W + (size_t)l * W_L;
;         if (r < 2 * I_W1) {
;             const bool second = r >= I_W1; if (second) r -= I_W1;
;             const float* W = a.in[second ? 14 : 2] + (size_t)l * D * NFF; const float* ks = a.in[second ? 13 : 1] + (size_t)l * D;
;             const int nblk = NFF / 32, kb = r / nblk, nb = r % nblk, n0 = 32 * nb;
;             const int dst = n0 < DFF ? (n0 / 128) * 256 + (n0 % 128) : ((n0 - DFF) / 128) * 256 + 128 + ((n0 - DFF) % 128);
;             tr_item(W, D, NFF, ks, (bf16*)(wl + (second ? W3_OFF : W1_OFF)), dst, scr, 64 * kb, n0, lane);
;             continue;
;         }
;         r -= 2 * I_W1;
;         if (r < 2 * I_W2) {
;             const bool second = r >= I_W2; if (second) r -= I_W2;
;             const float* W = a.in[second ? 15 : 3] + (size_t)l * DFF * D;
;             const int nblk = D / 32, kb = r / nblk, nb = r % nblk;
;             tr_item(W, DFF, D, nullptr, (bf16*)(wl + (second ? W4_OFF : W2_OFF)), 32 * nb, scr, 64 * kb, 32 * nb, lane);
;             continue;
;         }
;         r -= 2 * I_W2;
;         if (r < I_WIN) {
;             const float* W = a.in[5] + (size_t)l * D * INCOLS; const float* ks = a.in[4] + (size_t)l * D;
;             const int nblk = NPROJ / 32, kb = r / nblk, nb = r % nblk;
;             tr_item(W, D, INCOLS, ks, (bf16*)(wl + WIN_OFF), 32 * nb, scr, 64 * kb, 32 * nb, lane);
;             continue;
;         }
;         r -= I_WIN;
;         {
;             const float* W = a.in[12] + (size_t)l * D * D;
;             const int nblk = D / 32, kb = r / nblk, nb = r % nblk;
;             tr_item(W, D, D, nullptr, (bf16*)(wl + WOUT_OFF), 32 * nb, scr, 64 * kb, 32 * nb, lane);
;         }
.Lwq_top1:
	s_lshl_b32 s82, s28, 3
	s_add_u32 s82, s83, s82
	s_cmp_lt_u32 s82, 0x5100
	s_cbranch_scc0 .Lwq_last1
	s_cmp_ge_u32 s82, 0x2880
	s_cselect_b32 s0, 1, 0
	s_mul_i32 s1, s0, 0x2880
	s_sub_u32 s1, s82, s1
	s_mul_i32 s2, s0, 0x2880000
	s_add_u32 s68, s34, s2
	s_addc_u32 s69, s35, 0
	s_add_u32 s68, s68, 0x800000
	s_addc_u32 s69, s69, 0
	s_mov_b32 s31, 64
	s_cmp_lt_u32 s1, 0x1600
	s_cbranch_scc1 .Lwq_t0_3
	s_cmp_lt_u32 s1, 0x2100
	s_cbranch_scc1 .Lwq_t1_3
	s_cmp_lt_u32 s1, 0x2680
	s_cbranch_scc1 .Lwq_t2_3
	s_sub_u32 s1, s1, 0x2680
	s_and_b32 s3, s1, 15
	s_lshr_b32 s4, s1, 4
	s_lshl_b32 s5, s0, 22
	s_lshl_b32 s86, s3, 18
	s_add_u32 s5, s5, s86
	s_lshl_b32 s86, s4, 7
	s_add_u32 s5, s5, s86
	s_add_u32 s64, s20, s5
	s_addc_u32 s65, s21, 0
	s_mov_b32 s29, 0x1000
	s_mov_b32 s66, s38
	s_mov_b32 s67, s39
	s_mov_b32 s71, 0
	s_lshl_b32 s5, s4, 16
	s_lshl_b32 s86, s3, 7
	s_add_u32 s5, s5, s86
	s_add_u32 s5, s5, 0x1600000
	s_add_u32 s68, s68, s5
	s_addc_u32 s69, s69, 0
	s_mov_b32 s70, 0x800
	s_branch .Lwq_te_3
